# scan compute waves at priority 3 inside the chunk loop; L2 write-back dropped in the seams after P1/P6/P14
# baseline (speedup 1.0000x reference)
.LBB0_1545:
	s_ashr_i32 s0, s42, 2
	s_and_b32 s0, s0, -8
	s_and_b32 s1, s42, 7
	s_or_b32 s0, s0, s1
	s_cmp_gt_i32 s0, 11
	s_cbranch_scc1 .LBB0_1544
	s_mul_hi_i32 s4, s0, 0x2aaaaaab
	s_lshr_b32 s1, s4, 31
	s_add_i32 s4, s4, s1
	s_mul_i32 s1, s4, 6
	s_lshr_b32 s12, s42, 3
	s_sub_i32 s5, s0, s1
	s_mov_b64 s[0:1], -1
	s_and_b64 vcc, exec, s[10:11]
	s_cbranch_vccz .LBB0_1550
	s_and_b32 s0, s12, 3
	s_waitcnt vmcnt(10)
	v_lshl_or_b32 v0, s0, 7, v126
	s_lshl_b32 s0, s5, 7
	s_ashr_i32 s1, s0, 31
	s_mul_i32 s9, s4, 0x6800000
	s_lshl_b64 s[0:1], s[0:1], 1
	s_mul_hi_i32 s8, s4, 0x6800000
	s_add_u32 s0, s0, s9
	s_addc_u32 s1, s1, s8
	v_lshrrev_b32_e32 v2, 3, v0
	v_mov_b64_e32 v[0:1], s[0:1]
	s_movk_i32 s0, 0x1a00
	v_mad_u64_u32 v[0:1], s[0:1], v2, s0, v[0:1]
	s_waitcnt vmcnt(1)
	v_lshl_add_u64 v[48:49], v[122:123], 0, v[0:1]
	v_mov_b32_e32 v0, 0
	s_mov_b32 s0, 0
	v_mov_b32_e32 v32, 0
	v_mov_b32_e32 v33, 0
	v_mov_b32_e32 v34, 0
	v_mov_b32_e32 v35, 0
	v_mov_b32_e32 v36, 0
	v_mov_b32_e32 v37, 0
	v_mov_b32_e32 v38, 0
	v_mov_b32_e32 v39, 0
	v_mov_b32_e32 v40, 0
	v_mov_b32_e32 v41, 0
	v_mov_b32_e32 v42, 0
	v_mov_b32_e32 v43, 0
	v_mov_b32_e32 v44, 0
	v_mov_b32_e32 v45, 0
	v_mov_b32_e32 v46, 0
	v_mov_b32_e32 v47, 0
	v_mov_b32_e32 v1, v0
	v_mov_b32_e32 v2, v0
	v_mov_b32_e32 v3, v0
	v_mov_b32_e32 v4, v0
	v_mov_b32_e32 v5, v0
	v_mov_b32_e32 v6, v0
	v_mov_b32_e32 v7, v0
	v_mov_b32_e32 v8, v0
	v_mov_b32_e32 v9, v0
	v_mov_b32_e32 v10, v0
	v_mov_b32_e32 v11, v0
	v_mov_b32_e32 v12, v0
	v_mov_b32_e32 v13, v0
	v_mov_b32_e32 v14, v0
	v_mov_b32_e32 v15, v0
	v_mov_b32_e32 v16, v0
	v_mov_b32_e32 v17, v0
	v_mov_b32_e32 v18, v0
	v_mov_b32_e32 v19, v0
	v_mov_b32_e32 v20, v0
	v_mov_b32_e32 v21, v0
	v_mov_b32_e32 v22, v0
	v_mov_b32_e32 v23, v0
	v_mov_b32_e32 v24, v0
	v_mov_b32_e32 v25, v0
	v_mov_b32_e32 v26, v0
	v_mov_b32_e32 v27, v0
	v_mov_b32_e32 v28, v0
	v_mov_b32_e32 v29, v0
	v_mov_b32_e32 v30, v0
	v_mov_b32_e32 v31, v0
	v_mov_b32_e32 v51, v120
	v_add_u32_e32 v50, s79, v124
	v_mov_b32_e32 v214, 0x20000
	v_mov_b32_e32 v160, 0
	v_mov_b32_e32 v161, 0
	v_mov_b32_e32 v162, 0
	v_mov_b32_e32 v163, 0
	v_mov_b32_e32 v164, 0
	v_mov_b32_e32 v165, 0
	v_mov_b32_e32 v166, 0
	v_mov_b32_e32 v167, 0
	v_mov_b32_e32 v172, 0
	v_mov_b32_e32 v173, 0
	v_mov_b32_e32 v174, 0
	v_mov_b32_e32 v175, 0
	v_mov_b32_e32 v248, 0
	v_mov_b32_e32 v249, 0
	v_mov_b32_e32 v250, 0
	v_mov_b32_e32 v251, 0
	v_mov_b32_e32 v232, 0
	v_mov_b32_e32 v233, 0
	v_mov_b32_e32 v234, 0
	v_mov_b32_e32 v235, 0
	v_mov_b32_e32 v236, 0
	v_mov_b32_e32 v237, 0
	v_mov_b32_e32 v238, 0
	v_mov_b32_e32 v239, 0
	v_mov_b32_e32 v240, 0
	v_mov_b32_e32 v241, 0
	v_mov_b32_e32 v242, 0
	v_mov_b32_e32 v243, 0
	v_mov_b32_e32 v244, 0
	v_mov_b32_e32 v245, 0
	v_mov_b32_e32 v246, 0
	v_mov_b32_e32 v247, 0
	v_mov_b32_e32 v216, 0
	v_mov_b32_e32 v217, 0
	v_mov_b32_e32 v218, 0
	v_mov_b32_e32 v219, 0
	v_mov_b32_e32 v220, 0
	v_mov_b32_e32 v221, 0
	v_mov_b32_e32 v222, 0
	v_mov_b32_e32 v223, 0
	s_setprio 3
	s_waitcnt vmcnt(0)
	s_barrier
.LBB0_1548:
	ds_read_b128 v[52:55], v51 offset:0
	ds_read_b128 v[56:59], v51 offset:16384
	ds_read_b128 v[60:63], v51 offset:4096
	ds_read_b128 v[64:67], v51 offset:20480
	ds_read_b128 v[68:71], v51 offset:8192
	ds_read_b128 v[72:75], v51 offset:24576
	ds_read_b128 v[76:79], v51 offset:12288
	ds_read_b128 v[80:83], v51 offset:28672
	ds_read_b128 v[116:119], v50 offset:57344
	ds_read_b128 v[208:211], v50 offset:57360
	ds_read_b32 v212, v214
	ds_read_b128 v[84:87], v51 offset:1024
	ds_read_b128 v[88:91], v51 offset:17408
	ds_read_b128 v[92:95], v51 offset:5120
	ds_read_b128 v[96:99], v51 offset:21504
	v_mfma_f32_16x16x32_bf16 v[16:19], v[160:163], v[216:219], v[16:19]
	v_mfma_f32_16x16x32_bf16 v[16:19], v[164:167], v[220:223], v[16:19]
	v_cvt_pk_bf16_f32 v40, v8, v9
	v_mfma_f32_16x16x32_bf16 v[20:23], v[172:175], v[216:219], v[20:23]
	v_mfma_f32_16x16x32_bf16 v[20:23], v[248:251], v[220:223], v[20:23]
	v_cvt_pk_bf16_f32 v41, v10, v11
	v_mfma_f32_16x16x32_bf16 v[24:27], v[232:235], v[216:219], v[24:27]
	v_mfma_f32_16x16x32_bf16 v[24:27], v[236:239], v[220:223], v[24:27]
	v_cvt_pk_bf16_f32 v42, v12, v13
	v_mfma_f32_16x16x32_bf16 v[28:31], v[240:243], v[216:219], v[28:31]
	v_mfma_f32_16x16x32_bf16 v[28:31], v[244:247], v[220:223], v[28:31]
	v_cvt_pk_bf16_f32 v43, v14, v15
	s_waitcnt lgkmcnt(14)
	v_mfma_f32_16x16x32_bf16 v[176:179], v[52:55], v[44:47], 0
	ds_read_b128 v[100:103], v51 offset:9216
	s_waitcnt lgkmcnt(14)
	v_mfma_f32_16x16x32_bf16 v[192:195], v[56:59], v[44:47], 0
	ds_read_b128 v[104:107], v51 offset:25600
	s_waitcnt lgkmcnt(14)
	v_mfma_f32_16x16x32_bf16 v[180:183], v[60:63], v[44:47], 0
	ds_read_b128 v[108:111], v51 offset:13312
	v_cvt_pk_bf16_f32 v36, v16, v17
	v_cvt_pk_bf16_f32 v37, v18, v19
	s_waitcnt lgkmcnt(14)
	v_mfma_f32_16x16x32_bf16 v[196:199], v[64:67], v[44:47], 0
	ds_read_b128 v[112:115], v51 offset:29696
	v_cvt_pk_bf16_f32 v38, v20, v21
	v_cvt_pk_bf16_f32 v39, v22, v23
	s_waitcnt lgkmcnt(14)
	v_mfma_f32_16x16x32_bf16 v[184:187], v[68:71], v[44:47], 0
	v_cvt_pk_bf16_f32 v32, v24, v25
	v_cvt_pk_bf16_f32 v33, v26, v27
	s_waitcnt lgkmcnt(13)
	v_mfma_f32_16x16x32_bf16 v[200:203], v[72:75], v[44:47], 0
	v_cvt_pk_bf16_f32 v34, v28, v29
	v_cvt_pk_bf16_f32 v35, v30, v31
	s_waitcnt lgkmcnt(12)
	v_mfma_f32_16x16x32_bf16 v[188:191], v[76:79], v[44:47], 0
	s_waitcnt lgkmcnt(10)
	v_lshlrev_b32_e32 v232, 16, v116
	v_and_b32_e32 v233, 0xffff0000, v116
	v_mfma_f32_16x16x32_bf16 v[204:207], v[80:83], v[44:47], 0
	v_lshlrev_b32_e32 v234, 16, v117
	v_and_b32_e32 v235, 0xffff0000, v117
	ds_read_b128 v[128:131], v51 offset:2048
	ds_read_b128 v[132:135], v51 offset:18432
	ds_read_b128 v[136:139], v51 offset:6144
	ds_read_b128 v[140:143], v51 offset:22528
	s_waitcnt lgkmcnt(11)
	v_mfma_f32_16x16x32_bf16 v[176:179], v[84:87], v[40:43], v[176:179]
	ds_read_b128 v[144:147], v51 offset:10240
	v_lshlrev_b32_e32 v236, 16, v118
	v_and_b32_e32 v237, 0xffff0000, v118
	s_waitcnt lgkmcnt(11)
	v_mfma_f32_16x16x32_bf16 v[192:195], v[88:91], v[40:43], v[192:195]
	ds_read_b128 v[148:151], v51 offset:26624
	v_lshlrev_b32_e32 v238, 16, v119
	v_and_b32_e32 v239, 0xffff0000, v119
	s_waitcnt lgkmcnt(11)
	v_mfma_f32_16x16x32_bf16 v[180:183], v[92:95], v[40:43], v[180:183]
	ds_read_b128 v[152:155], v51 offset:14336
	v_lshlrev_b32_e32 v240, 16, v208
	v_and_b32_e32 v241, 0xffff0000, v208
	s_waitcnt lgkmcnt(11)
	v_mfma_f32_16x16x32_bf16 v[196:199], v[96:99], v[40:43], v[196:199]
	ds_read_b128 v[156:159], v51 offset:30720
	v_lshlrev_b32_e32 v242, 16, v209
	v_and_b32_e32 v243, 0xffff0000, v209
	s_waitcnt lgkmcnt(11)
	v_mfma_f32_16x16x32_bf16 v[184:187], v[100:103], v[40:43], v[184:187]
	v_lshlrev_b32_e32 v244, 16, v210
	v_and_b32_e32 v245, 0xffff0000, v210
	s_waitcnt lgkmcnt(10)
	v_mfma_f32_16x16x32_bf16 v[200:203], v[104:107], v[40:43], v[200:203]
	v_lshlrev_b32_e32 v246, 16, v211
	v_and_b32_e32 v247, 0xffff0000, v211
	s_waitcnt lgkmcnt(9)
	v_mfma_f32_16x16x32_bf16 v[188:191], v[108:111], v[40:43], v[188:191]
	v_mul_f32_e32 v0, v212, v0
	v_mul_f32_e32 v1, v212, v1
	s_waitcnt lgkmcnt(8)
	v_mfma_f32_16x16x32_bf16 v[204:207], v[112:115], v[40:43], v[204:207]
	v_mul_f32_e32 v2, v212, v2
	v_mul_f32_e32 v3, v212, v3
	ds_read_b128 v[52:55], v51 offset:3072
	ds_read_b128 v[56:59], v51 offset:7168
	ds_read_b128 v[60:63], v51 offset:11264
	ds_read_b128 v[64:67], v51 offset:15360
	s_waitcnt lgkmcnt(11)
	v_mfma_f32_16x16x32_bf16 v[176:179], v[128:131], v[36:39], v[176:179]
	ds_read_b128 v[68:71], v51 offset:19456
	v_mul_f32_e32 v4, v212, v4
	v_mul_f32_e32 v5, v212, v5
	s_waitcnt lgkmcnt(11)
	v_mfma_f32_16x16x32_bf16 v[192:195], v[132:135], v[36:39], v[192:195]
	ds_read_b128 v[72:75], v51 offset:23552
	v_mul_f32_e32 v6, v212, v6
	v_mul_f32_e32 v7, v212, v7
	s_waitcnt lgkmcnt(11)
	v_mfma_f32_16x16x32_bf16 v[180:183], v[136:139], v[36:39], v[180:183]
	ds_read_b128 v[76:79], v51 offset:27648
	v_mul_f32_e32 v8, v212, v8
	v_mul_f32_e32 v9, v212, v9
	s_waitcnt lgkmcnt(11)
	v_mfma_f32_16x16x32_bf16 v[196:199], v[140:143], v[36:39], v[196:199]
	ds_read_b128 v[80:83], v51 offset:31744
	v_mul_f32_e32 v10, v212, v10
	v_mul_f32_e32 v11, v212, v11
	s_waitcnt lgkmcnt(11)
	v_mfma_f32_16x16x32_bf16 v[184:187], v[144:147], v[36:39], v[184:187]
	v_mul_f32_e32 v12, v212, v12
	v_mul_f32_e32 v13, v212, v13
	s_waitcnt lgkmcnt(10)
	v_mfma_f32_16x16x32_bf16 v[200:203], v[148:151], v[36:39], v[200:203]
	v_mul_f32_e32 v14, v212, v14
	v_mul_f32_e32 v15, v212, v15
	s_waitcnt lgkmcnt(9)
	v_mfma_f32_16x16x32_bf16 v[188:191], v[152:155], v[36:39], v[188:191]
	v_mul_f32_e32 v16, v212, v16
	v_mul_f32_e32 v17, v212, v17
	s_waitcnt lgkmcnt(8)
	v_mfma_f32_16x16x32_bf16 v[204:207], v[156:159], v[36:39], v[204:207]
	v_mul_f32_e32 v18, v212, v18
	v_mul_f32_e32 v19, v212, v19
	ds_read_b128 v[84:87], v51 offset:49152
	ds_read_b128 v[88:91], v51 offset:51200
	ds_read_b128 v[92:95], v51 offset:53248
	ds_read_b128 v[96:99], v51 offset:55296
	s_waitcnt lgkmcnt(11)
	v_mfma_f32_16x16x32_bf16 v[176:179], v[52:55], v[32:35], v[176:179]
	ds_read_b128 v[100:103], v51 offset:50176
	v_mul_f32_e32 v20, v212, v20
	v_mul_f32_e32 v21, v212, v21
	v_mul_f32_e32 v22, v212, v22
	s_waitcnt lgkmcnt(11)
	v_mfma_f32_16x16x32_bf16 v[180:183], v[56:59], v[32:35], v[180:183]
	ds_read_b128 v[104:107], v51 offset:52224
	v_mul_f32_e32 v23, v212, v23
	v_mul_f32_e32 v24, v212, v24
	v_mul_f32_e32 v25, v212, v25
	s_waitcnt lgkmcnt(11)
	v_mfma_f32_16x16x32_bf16 v[184:187], v[60:63], v[32:35], v[184:187]
	ds_read_b128 v[108:111], v51 offset:54272
	v_mul_f32_e32 v26, v212, v26
	v_mul_f32_e32 v27, v212, v27
	v_mul_f32_e32 v28, v212, v28
	s_waitcnt lgkmcnt(11)
	v_mfma_f32_16x16x32_bf16 v[188:191], v[64:67], v[32:35], v[188:191]
	ds_read_b128 v[112:115], v51 offset:56320
	v_mul_f32_e32 v29, v212, v29
	v_mul_f32_e32 v30, v212, v30
	v_mul_f32_e32 v31, v212, v31
	s_waitcnt lgkmcnt(11)
	v_mfma_f32_16x16x32_bf16 v[192:195], v[68:71], v[32:35], v[192:195]
	v_sub_f32_e32 v232, v232, v176
	v_sub_f32_e32 v233, v233, v177
	v_sub_f32_e32 v234, v234, v178
	v_sub_f32_e32 v235, v235, v179
	s_waitcnt lgkmcnt(10)
	v_mfma_f32_16x16x32_bf16 v[196:199], v[72:75], v[32:35], v[196:199]
	v_sub_f32_e32 v236, v236, v180
	v_sub_f32_e32 v237, v237, v181
	v_sub_f32_e32 v238, v238, v182
	v_sub_f32_e32 v239, v239, v183
	s_waitcnt lgkmcnt(9)
	v_mfma_f32_16x16x32_bf16 v[200:203], v[76:79], v[32:35], v[200:203]
	v_cvt_pk_bf16_f32 v216, v232, v233
	v_cvt_pk_bf16_f32 v217, v234, v235
	v_cvt_pk_bf16_f32 v218, v236, v237
	v_cvt_pk_bf16_f32 v219, v238, v239
	s_waitcnt lgkmcnt(8)
	v_mfma_f32_16x16x32_bf16 v[204:207], v[80:83], v[32:35], v[204:207]
	v_sub_f32_e32 v240, v240, v184
	v_sub_f32_e32 v241, v241, v185
	v_sub_f32_e32 v242, v242, v186
	v_sub_f32_e32 v243, v243, v187
	v_sub_f32_e32 v244, v244, v188
	v_sub_f32_e32 v245, v245, v189
	v_sub_f32_e32 v246, v246, v190
	v_sub_f32_e32 v247, v247, v191
	ds_read_b128 v[128:131], v51 offset:32768
	ds_read_b128 v[132:135], v51 offset:33792
	ds_read_b128 v[136:139], v51 offset:34816
	ds_read_b128 v[140:143], v51 offset:35840
	ds_read_b128 v[144:147], v51 offset:36864
	ds_read_b128 v[148:151], v51 offset:37888
	s_waitcnt lgkmcnt(13)
	v_mfma_f32_16x16x32_bf16 v[192:195], v[84:87], v[216:219], v[192:195]
	v_cvt_pk_bf16_f32 v220, v240, v241
	v_cvt_pk_bf16_f32 v221, v242, v243
	s_waitcnt lgkmcnt(12)
	v_mfma_f32_16x16x32_bf16 v[196:199], v[88:91], v[216:219], v[196:199]
	v_cvt_pk_bf16_f32 v222, v244, v245
	v_cvt_pk_bf16_f32 v223, v246, v247
	s_waitcnt lgkmcnt(11)
	v_mfma_f32_16x16x32_bf16 v[200:203], v[92:95], v[216:219], v[200:203]
	ds_read_b128 v[152:155], v51 offset:38912
	s_waitcnt lgkmcnt(11)
	v_mfma_f32_16x16x32_bf16 v[204:207], v[96:99], v[216:219], v[204:207]
	ds_read_b128 v[156:159], v51 offset:39936
	s_waitcnt lgkmcnt(11)
	v_mfma_f32_16x16x32_bf16 v[192:195], v[100:103], v[220:223], v[192:195]
	s_waitcnt lgkmcnt(10)
	v_mfma_f32_16x16x32_bf16 v[196:199], v[104:107], v[220:223], v[196:199]
	s_waitcnt lgkmcnt(9)
	v_mfma_f32_16x16x32_bf16 v[200:203], v[108:111], v[220:223], v[200:203]
	s_waitcnt lgkmcnt(8)
	v_mfma_f32_16x16x32_bf16 v[204:207], v[112:115], v[220:223], v[204:207]
	ds_read_b128 v[160:163], v51 offset:40960
	ds_read_b128 v[164:167], v51 offset:41984
	ds_read_b128 v[172:175], v51 offset:43008
	ds_read_b128 v[248:251], v51 offset:44032
	ds_read_b128 v[232:235], v51 offset:45056
	ds_read_b128 v[236:239], v51 offset:46080
	ds_read_b128 v[240:243], v51 offset:47104
	s_add_i32 s0, s0, 1
	s_and_b32 s1, s0, 1
	s_lshl_b32 s8, s1, 16
	s_lshl_b32 s1, s1, 2
	s_add_i32 s9, s8, s79
	s_add_i32 s1, s1, 0x20000
	s_waitcnt lgkmcnt(14)
	v_mfma_f32_16x16x32_bf16 v[0:3], v[128:131], v[216:219], v[0:3]
	ds_read_b128 v[244:247], v51 offset:48128
	s_waitcnt lgkmcnt(14)
	v_mfma_f32_16x16x32_bf16 v[0:3], v[132:135], v[220:223], v[0:3]
	v_add_u32_e32 v50, s9, v124
	v_mov_b32_e32 v214, s1
	s_waitcnt lgkmcnt(13)
	v_mfma_f32_16x16x32_bf16 v[4:7], v[136:139], v[216:219], v[4:7]
	s_waitcnt lgkmcnt(12)
	v_mfma_f32_16x16x32_bf16 v[4:7], v[140:143], v[220:223], v[4:7]
	v_cvt_pk_bf16_f32 v224, v192, v193
	v_cvt_pk_bf16_f32 v225, v194, v195
	v_cvt_pk_bf16_f32 v226, v196, v197
	v_cvt_pk_bf16_f32 v227, v198, v199
	s_waitcnt lgkmcnt(11)
	v_mfma_f32_16x16x32_bf16 v[8:11], v[144:147], v[216:219], v[8:11]
	s_waitcnt lgkmcnt(10)
	v_mfma_f32_16x16x32_bf16 v[8:11], v[148:151], v[220:223], v[8:11]
	v_cvt_pk_bf16_f32 v228, v200, v201
	v_cvt_pk_bf16_f32 v229, v202, v203
	v_cvt_pk_bf16_f32 v230, v204, v205
	v_cvt_pk_bf16_f32 v231, v206, v207
	global_store_dwordx4 v[48:49], v[224:227], off
	s_waitcnt lgkmcnt(9)
	v_mfma_f32_16x16x32_bf16 v[12:15], v[152:155], v[216:219], v[12:15]
	v_cvt_pk_bf16_f32 v44, v0, v1
	v_cvt_pk_bf16_f32 v45, v2, v3
	v_cvt_pk_bf16_f32 v46, v4, v5
	v_cvt_pk_bf16_f32 v47, v6, v7
	global_store_dwordx4 v[48:49], v[228:231], off offset:16
	v_add_u32_e32 v51, s8, v120
	s_mov_b64 s[8:9], 0x68000
	v_lshl_add_u64 v[48:49], v[48:49], 0, s[8:9]
	s_cmpk_lg_i32 s0, 0x100
	s_waitcnt lgkmcnt(0)
	v_mfma_f32_16x16x32_bf16 v[12:15], v[156:159], v[220:223], v[12:15]
	s_barrier
	s_cbranch_scc1 .LBB0_1548
	s_setprio 0
	s_mov_b64 s[0:1], 0
